# gate/up epilogue: per-row 1/rms computed cooperatively (4 loads/thread, LDS table) instead of 8 serialized load+shuffle+sqrt/div chains per lane
# speedup vs baseline: 1.3315x; 1.3315x over previous
.LBB0_607:
	v_readlane_b32 s6, v253, 4
	v_readlane_b32 s7, v253, 5
	v_lshrrev_b32_e32 v135, 1, v146
	s_load_dwordx2 s[22:23], s[6:7], 0x98
	v_and_b32_e32 v136, 1, v146
	v_lshl_add_u32 v134, s5, 8, v135
	v_lshlrev_b32_e32 v134, 7, v134
	v_lshl_or_b32 v134, v136, 6, v134
	v_lshl_add_u32 v162, s5, 8, v149
	v_lshl_or_b32 v164, s4, 7, v177
	s_waitcnt lgkmcnt(0)
	s_add_u32 s4, s22, 0x1a700000
	s_addc_u32 s5, s23, 0
	global_load_dwordx4 v[236:239], v134, s[4:5]
	global_load_dwordx4 v[240:243], v134, s[4:5] offset:16
	global_load_dwordx4 v[244:247], v134, s[4:5] offset:32
	global_load_dwordx4 v[194:197], v134, s[4:5] offset:48
	s_mov_b32 s18, 0xf800000
	v_ashrrev_i32_e32 v165, 31, v164
	v_or_b32_e32 v168, 16, v162
	v_or_b32_e32 v166, 32, v162
	v_or_b32_e32 v170, 48, v162
	v_add_u32_e32 v172, 0x80, v162
	v_add_u32_e32 v184, 0x90, v162
	v_add_u32_e32 v188, 0xa0, v162
	v_add_u32_e32 v192, 0xb0, v162
	v_lshl_add_u64 v[132:133], v[164:165], 1, s[22:23]
	v_lshlrev_b32_e32 v135, 2, v135
	v_add_u32_e32 v135, 0x20240, v135
	s_waitcnt vmcnt(0)
	v_pk_add_f32 v[238:239], v[238:239], v[242:243]
	v_pk_add_f32 v[236:237], v[236:237], v[240:241]
	v_pk_add_f32 v[246:247], v[246:247], v[196:197]
	v_pk_add_f32 v[244:245], v[244:245], v[194:195]
	s_mov_b64 s[4:5], 0x12f00000
	v_add_f32_e32 v236, v236, v237
	v_add_f32_e32 v238, v238, v239
	v_add_f32_e32 v244, v244, v245
	v_add_f32_e32 v246, v246, v247
	v_add_f32_e32 v236, v236, v238
	v_add_f32_e32 v244, v244, v246
	v_lshl_add_u64 v[132:133], v[132:133], 0, s[4:5]
	v_add_f32_e32 v236, v236, v244
	s_nop 1
	v_mov_b32_dpp v237, v236 quad_perm:[1,0,3,2] row_mask:0xf bank_mask:0xf
	s_nop 0
	v_add_f32_e32 v236, v236, v237
	v_fmamk_f32 v137, v236, 0x3a000000, v204
	v_cmp_gt_f32_e32 vcc, s18, v137
	v_mul_f32_e32 v154, 0x4f800000, v137
	s_nop 0
	v_cndmask_b32_e32 v137, v137, v154, vcc
	v_sqrt_f32_e32 v154, v137
	s_nop 0
	v_add_u32_e32 v155, -1, v154
	v_fma_f32 v156, -v155, v154, v137
	v_cmp_ge_f32_e64 s[6:7], 0, v156
	v_add_u32_e32 v156, 1, v154
	s_nop 0
	v_cndmask_b32_e64 v155, v154, v155, s[6:7]
	v_fma_f32 v154, -v156, v154, v137
	v_cmp_lt_f32_e64 s[6:7], 0, v154
	s_nop 1
	v_cndmask_b32_e64 v154, v155, v156, s[6:7]
	v_mul_f32_e32 v155, 0x37800000, v154
	v_cndmask_b32_e32 v154, v154, v155, vcc
	v_cmp_class_f32_e32 vcc, v137, v205
	s_nop 1
	v_cndmask_b32_e32 v137, v154, v137, vcc
	v_div_scale_f32 v154, s[4:5], v137, v137, 1.0
	v_rcp_f32_e32 v155, v154
	s_nop 0
	v_fma_f32 v156, -v154, v155, 1.0
	v_fmac_f32_e32 v155, v156, v155
	v_div_scale_f32 v156, vcc, 1.0, v137, 1.0
	v_mul_f32_e32 v157, v156, v155
	v_fma_f32 v198, -v154, v157, v156
	v_fmac_f32_e32 v157, v198, v155
	v_fma_f32 v154, -v154, v157, v156
	v_div_fmas_f32 v154, v154, v155, v157
	v_div_fixup_f32 v199, v154, v137, 1.0
	ds_write_b32 v135, v199
	v_lshlrev_b32_e32 v134, 2, v149
	v_add_u32_e32 v134, 0x20240, v134
	s_waitcnt lgkmcnt(0)
	s_barrier
	ds_read_b32 v180, v134
	ds_read_b32 v176, v134 offset:64
	ds_read_b32 v174, v134 offset:128
	ds_read_b32 v178, v134 offset:192
	ds_read_b32 v182, v134 offset:512
	ds_read_b32 v186, v134 offset:576
	ds_read_b32 v190, v134 offset:640
	ds_read_b32 v130, v134 offset:704
	s_movk_i32 s6, 0x2c00
	s_waitcnt lgkmcnt(0)
	v_pk_mul_f32 v[126:127], v[126:127], v[180:181] op_sel_hi:[1,0]
	v_pk_mul_f32 v[118:119], v[118:119], v[180:181] op_sel_hi:[1,0]
	v_pk_mul_f32 v[128:129], v[128:129], v[180:181] op_sel_hi:[1,0]
	v_pk_mul_f32 v[120:121], v[120:121], v[180:181] op_sel_hi:[1,0]
	v_pk_mul_f32 v[122:123], v[122:123], v[180:181] op_sel_hi:[1,0]
	v_pk_mul_f32 v[124:125], v[124:125], v[180:181] op_sel_hi:[1,0]
	v_pk_mul_f32 v[110:111], v[110:111], v[176:177] op_sel_hi:[1,0]
	v_pk_mul_f32 v[102:103], v[102:103], v[176:177] op_sel_hi:[1,0]
	v_pk_mul_f32 v[112:113], v[112:113], v[176:177] op_sel_hi:[1,0]
	v_pk_mul_f32 v[104:105], v[104:105], v[176:177] op_sel_hi:[1,0]
	v_pk_mul_f32 v[106:107], v[106:107], v[176:177] op_sel_hi:[1,0]
	v_pk_mul_f32 v[108:109], v[108:109], v[176:177] op_sel_hi:[1,0]
	v_pk_mul_f32 v[94:95], v[94:95], v[174:175] op_sel_hi:[1,0]
	v_pk_mul_f32 v[86:87], v[86:87], v[174:175] op_sel_hi:[1,0]
	v_pk_mul_f32 v[96:97], v[96:97], v[174:175] op_sel_hi:[1,0]
	v_pk_mul_f32 v[88:89], v[88:89], v[174:175] op_sel_hi:[1,0]
	v_pk_mul_f32 v[90:91], v[90:91], v[174:175] op_sel_hi:[1,0]
	v_pk_mul_f32 v[92:93], v[92:93], v[174:175] op_sel_hi:[1,0]
	v_pk_mul_f32 v[78:79], v[78:79], v[178:179] op_sel_hi:[1,0]
	v_pk_mul_f32 v[70:71], v[70:71], v[178:179] op_sel_hi:[1,0]
	v_pk_mul_f32 v[80:81], v[80:81], v[178:179] op_sel_hi:[1,0]
	v_pk_mul_f32 v[72:73], v[72:73], v[178:179] op_sel_hi:[1,0]
	v_pk_mul_f32 v[74:75], v[74:75], v[178:179] op_sel_hi:[1,0]
	v_pk_mul_f32 v[76:77], v[76:77], v[178:179] op_sel_hi:[1,0]
	v_pk_mul_f32 v[62:63], v[62:63], v[182:183] op_sel_hi:[1,0]
	v_pk_mul_f32 v[54:55], v[54:55], v[182:183] op_sel_hi:[1,0]
	v_pk_mul_f32 v[64:65], v[64:65], v[182:183] op_sel_hi:[1,0]
	v_pk_mul_f32 v[56:57], v[56:57], v[182:183] op_sel_hi:[1,0]
	v_pk_mul_f32 v[58:59], v[58:59], v[182:183] op_sel_hi:[1,0]
	v_pk_mul_f32 v[60:61], v[60:61], v[182:183] op_sel_hi:[1,0]
	v_pk_mul_f32 v[46:47], v[46:47], v[186:187] op_sel_hi:[1,0]
	v_pk_mul_f32 v[38:39], v[38:39], v[186:187] op_sel_hi:[1,0]
	v_pk_mul_f32 v[48:49], v[48:49], v[186:187] op_sel_hi:[1,0]
	v_pk_mul_f32 v[40:41], v[40:41], v[186:187] op_sel_hi:[1,0]
	v_pk_mul_f32 v[42:43], v[42:43], v[186:187] op_sel_hi:[1,0]
	v_pk_mul_f32 v[44:45], v[44:45], v[186:187] op_sel_hi:[1,0]
	v_pk_mul_f32 v[30:31], v[30:31], v[190:191] op_sel_hi:[1,0]
	v_pk_mul_f32 v[22:23], v[22:23], v[190:191] op_sel_hi:[1,0]
	v_pk_mul_f32 v[32:33], v[32:33], v[190:191] op_sel_hi:[1,0]
	v_pk_mul_f32 v[24:25], v[24:25], v[190:191] op_sel_hi:[1,0]
	v_pk_mul_f32 v[26:27], v[26:27], v[190:191] op_sel_hi:[1,0]
	v_pk_mul_f32 v[28:29], v[28:29], v[190:191] op_sel_hi:[1,0]
	v_pk_mul_f32 v[136:137], v[116:117], v[180:181] op_sel_hi:[1,0]
	v_pk_mul_f32 v[116:117], v[114:115], v[180:181] op_sel_hi:[1,0]
	v_mul_f32_e32 v114, 0xbfb8aa3b, v126
	v_mul_f32_e32 v115, 0xbfb8aa3b, v127
	v_exp_f32_e32 v114, v114
	v_exp_f32_e32 v115, v115
	v_mad_i64_i32 v[134:135], s[4:5], v162, s6, v[132:133]
	v_add_f32_e32 v114, 1.0, v114
	v_add_f32_e32 v115, 1.0, v115
	v_rcp_f32_e32 v114, v114
	v_rcp_f32_e32 v115, v115
	s_nop 0
	v_pk_mul_f32 v[114:115], v[126:127], v[114:115]
	s_nop 0
	v_pk_mul_f32 v[114:115], v[118:119], v[114:115]
	s_nop 0
	v_cvt_pk_bf16_f32 v114, v114, v115
	v_mul_f32_e32 v115, 0xbfb8aa3b, v128
	v_exp_f32_e32 v115, v115
	s_nop 0
	v_add_f32_e32 v115, 1.0, v115
	v_rcp_f32_e32 v118, v115
	v_mul_f32_e32 v115, 0xbfb8aa3b, v129
	v_exp_f32_e32 v115, v115
	s_nop 0
	v_add_f32_e32 v115, 1.0, v115
	v_rcp_f32_e32 v119, v115
	s_nop 0
	v_pk_mul_f32 v[118:119], v[128:129], v[118:119]
	s_nop 0
	v_pk_mul_f32 v[118:119], v[120:121], v[118:119]
	s_nop 0
	v_cvt_pk_bf16_f32 v115, v118, v119
	v_mul_f32_e32 v118, 0xbfb8aa3b, v122
	v_mul_f32_e32 v119, 0xbfb8aa3b, v123
	v_exp_f32_e32 v118, v118
	v_exp_f32_e32 v119, v119
	s_nop 0
	v_add_f32_e32 v118, 1.0, v118
	v_add_f32_e32 v119, 1.0, v119
	v_rcp_f32_e32 v118, v118
	v_rcp_f32_e32 v119, v119
	s_nop 0
	v_pk_mul_f32 v[118:119], v[122:123], v[118:119]
	s_nop 0
	v_pk_mul_f32 v[116:117], v[116:117], v[118:119]
	s_nop 0
	v_cvt_pk_bf16_f32 v116, v116, v117
	v_mul_f32_e32 v117, 0xbfb8aa3b, v124
	v_exp_f32_e32 v117, v117
	s_nop 0
	v_add_f32_e32 v117, 1.0, v117
	v_rcp_f32_e32 v118, v117
	v_mul_f32_e32 v117, 0xbfb8aa3b, v125
	v_exp_f32_e32 v117, v117
	s_nop 0
	v_add_f32_e32 v117, 1.0, v117
	v_rcp_f32_e32 v119, v117
	s_nop 0
	v_pk_mul_f32 v[118:119], v[124:125], v[118:119]
	s_nop 0
	v_pk_mul_f32 v[118:119], v[136:137], v[118:119]
	s_nop 0
	v_cvt_pk_bf16_f32 v117, v118, v119
	global_store_dwordx4 v[134:135], v[114:117], off
	s_nop 1
	v_pk_mul_f32 v[14:15], v[14:15], v[130:131] op_sel_hi:[1,0]
	v_pk_mul_f32 v[116:117], v[100:101], v[176:177] op_sel_hi:[1,0]
	v_pk_mul_f32 v[100:101], v[98:99], v[176:177] op_sel_hi:[1,0]
	v_mul_f32_e32 v98, 0xbfb8aa3b, v110
	v_mul_f32_e32 v99, 0xbfb8aa3b, v111
	v_exp_f32_e32 v98, v98
	v_exp_f32_e32 v99, v99
	v_mad_i64_i32 v[114:115], s[4:5], v168, s6, v[132:133]
	v_add_f32_e32 v98, 1.0, v98
	v_add_f32_e32 v99, 1.0, v99
	v_rcp_f32_e32 v98, v98
	v_rcp_f32_e32 v99, v99
	v_pk_mul_f32 v[6:7], v[6:7], v[130:131] op_sel_hi:[1,0]
	v_pk_mul_f32 v[16:17], v[16:17], v[130:131] op_sel_hi:[1,0]
	v_pk_mul_f32 v[8:9], v[8:9], v[130:131] op_sel_hi:[1,0]
	v_pk_mul_f32 v[98:99], v[110:111], v[98:99]
	v_pk_mul_f32 v[10:11], v[10:11], v[130:131] op_sel_hi:[1,0]
	v_pk_mul_f32 v[98:99], v[102:103], v[98:99]
	v_pk_mul_f32 v[12:13], v[12:13], v[130:131] op_sel_hi:[1,0]
	v_cvt_pk_bf16_f32 v98, v98, v99
	v_mul_f32_e32 v99, 0xbfb8aa3b, v112
	v_exp_f32_e32 v99, v99
	s_andn2_b64 vcc, exec, s[38:39]
	v_add_f32_e32 v99, 1.0, v99
	v_rcp_f32_e32 v102, v99
	v_mul_f32_e32 v99, 0xbfb8aa3b, v113
	v_exp_f32_e32 v99, v99
	s_nop 0
	v_add_f32_e32 v99, 1.0, v99
	v_rcp_f32_e32 v103, v99
	s_nop 0
	v_pk_mul_f32 v[102:103], v[112:113], v[102:103]
	s_nop 0
	v_pk_mul_f32 v[102:103], v[104:105], v[102:103]
	s_nop 0
	v_cvt_pk_bf16_f32 v99, v102, v103
	v_mul_f32_e32 v102, 0xbfb8aa3b, v106
	v_mul_f32_e32 v103, 0xbfb8aa3b, v107
	v_exp_f32_e32 v102, v102
	v_exp_f32_e32 v103, v103
	v_add_f32_e32 v102, 1.0, v102
	v_add_f32_e32 v103, 1.0, v103
	v_rcp_f32_e32 v102, v102
	v_rcp_f32_e32 v103, v103
	s_nop 0
	v_pk_mul_f32 v[102:103], v[106:107], v[102:103]
	s_nop 0
	v_pk_mul_f32 v[100:101], v[100:101], v[102:103]
	s_nop 0
	v_cvt_pk_bf16_f32 v100, v100, v101
	v_mul_f32_e32 v101, 0xbfb8aa3b, v108
	v_exp_f32_e32 v101, v101
	s_nop 0
	v_add_f32_e32 v101, 1.0, v101
	v_rcp_f32_e32 v102, v101
	v_mul_f32_e32 v101, 0xbfb8aa3b, v109
	v_exp_f32_e32 v101, v101
	s_nop 0
	v_add_f32_e32 v101, 1.0, v101
	v_rcp_f32_e32 v103, v101
	s_nop 0
	v_pk_mul_f32 v[102:103], v[108:109], v[102:103]
	s_nop 0
	v_pk_mul_f32 v[102:103], v[116:117], v[102:103]
	s_nop 0
	v_cvt_pk_bf16_f32 v101, v102, v103
	global_store_dwordx4 v[114:115], v[98:101], off
	s_nop 1
	v_pk_mul_f32 v[100:101], v[84:85], v[174:175] op_sel_hi:[1,0]
	v_pk_mul_f32 v[84:85], v[82:83], v[174:175] op_sel_hi:[1,0]
	v_mul_f32_e32 v82, 0xbfb8aa3b, v94
	v_mul_f32_e32 v83, 0xbfb8aa3b, v95
	v_exp_f32_e32 v82, v82
	v_exp_f32_e32 v83, v83
	v_mad_i64_i32 v[98:99], s[4:5], v166, s6, v[132:133]
	v_add_f32_e32 v82, 1.0, v82
	v_add_f32_e32 v83, 1.0, v83
	v_rcp_f32_e32 v82, v82
	v_rcp_f32_e32 v83, v83
	s_nop 0
	v_pk_mul_f32 v[82:83], v[94:95], v[82:83]
	s_nop 0
	v_pk_mul_f32 v[82:83], v[86:87], v[82:83]
	s_nop 0
	v_cvt_pk_bf16_f32 v82, v82, v83
	v_mul_f32_e32 v83, 0xbfb8aa3b, v96
	v_exp_f32_e32 v83, v83
	s_nop 0
	v_add_f32_e32 v83, 1.0, v83
	v_rcp_f32_e32 v86, v83
	v_mul_f32_e32 v83, 0xbfb8aa3b, v97
	v_exp_f32_e32 v83, v83
	s_nop 0
	v_add_f32_e32 v83, 1.0, v83
	v_rcp_f32_e32 v87, v83
	s_nop 0
	v_pk_mul_f32 v[86:87], v[96:97], v[86:87]
	s_nop 0
	v_pk_mul_f32 v[86:87], v[88:89], v[86:87]
	s_nop 0
	v_cvt_pk_bf16_f32 v83, v86, v87
	v_mul_f32_e32 v86, 0xbfb8aa3b, v90
	v_mul_f32_e32 v87, 0xbfb8aa3b, v91
	v_exp_f32_e32 v86, v86
	v_exp_f32_e32 v87, v87
	v_add_f32_e32 v86, 1.0, v86
	v_add_f32_e32 v87, 1.0, v87
	v_rcp_f32_e32 v86, v86
	v_rcp_f32_e32 v87, v87
	s_nop 0
	v_pk_mul_f32 v[86:87], v[90:91], v[86:87]
	s_nop 0
	v_pk_mul_f32 v[84:85], v[84:85], v[86:87]
	s_nop 0
	v_cvt_pk_bf16_f32 v84, v84, v85
	v_mul_f32_e32 v85, 0xbfb8aa3b, v92
	v_exp_f32_e32 v85, v85
	s_nop 0
	v_add_f32_e32 v85, 1.0, v85
	v_rcp_f32_e32 v86, v85
	v_mul_f32_e32 v85, 0xbfb8aa3b, v93
	v_exp_f32_e32 v85, v85
	s_nop 0
	v_add_f32_e32 v85, 1.0, v85
	v_rcp_f32_e32 v87, v85
	s_nop 0
	v_pk_mul_f32 v[86:87], v[92:93], v[86:87]
	s_nop 0
	v_pk_mul_f32 v[86:87], v[100:101], v[86:87]
	s_nop 0
	v_cvt_pk_bf16_f32 v85, v86, v87
	global_store_dwordx4 v[98:99], v[82:85], off
	s_nop 1
	v_pk_mul_f32 v[84:85], v[68:69], v[178:179] op_sel_hi:[1,0]
	v_pk_mul_f32 v[68:69], v[66:67], v[178:179] op_sel_hi:[1,0]
	v_mul_f32_e32 v66, 0xbfb8aa3b, v78
	v_mul_f32_e32 v67, 0xbfb8aa3b, v79
	v_exp_f32_e32 v66, v66
	v_exp_f32_e32 v67, v67
	v_mad_i64_i32 v[82:83], s[4:5], v170, s6, v[132:133]
	v_add_f32_e32 v66, 1.0, v66
	v_add_f32_e32 v67, 1.0, v67
	v_rcp_f32_e32 v66, v66
	v_rcp_f32_e32 v67, v67
	s_nop 0
	v_pk_mul_f32 v[66:67], v[78:79], v[66:67]
	s_nop 0
	v_pk_mul_f32 v[66:67], v[70:71], v[66:67]
	s_nop 0
	v_cvt_pk_bf16_f32 v66, v66, v67
	v_mul_f32_e32 v67, 0xbfb8aa3b, v80
	v_exp_f32_e32 v67, v67
	s_nop 0
	v_add_f32_e32 v67, 1.0, v67
	v_rcp_f32_e32 v70, v67
	v_mul_f32_e32 v67, 0xbfb8aa3b, v81
	v_exp_f32_e32 v67, v67
	s_nop 0
	v_add_f32_e32 v67, 1.0, v67
	v_rcp_f32_e32 v71, v67
	s_nop 0
	v_pk_mul_f32 v[70:71], v[80:81], v[70:71]
	s_nop 0
	v_pk_mul_f32 v[70:71], v[72:73], v[70:71]
	s_nop 0
	v_cvt_pk_bf16_f32 v67, v70, v71
	v_mul_f32_e32 v70, 0xbfb8aa3b, v74
	v_mul_f32_e32 v71, 0xbfb8aa3b, v75
	v_exp_f32_e32 v70, v70
	v_exp_f32_e32 v71, v71
	v_add_f32_e32 v70, 1.0, v70
	v_add_f32_e32 v71, 1.0, v71
	v_rcp_f32_e32 v70, v70
	v_rcp_f32_e32 v71, v71
	s_nop 0
	v_pk_mul_f32 v[70:71], v[74:75], v[70:71]
	s_nop 0
	v_pk_mul_f32 v[68:69], v[68:69], v[70:71]
	s_nop 0
	v_cvt_pk_bf16_f32 v68, v68, v69
	v_mul_f32_e32 v69, 0xbfb8aa3b, v76
	v_exp_f32_e32 v69, v69
	s_nop 0
	v_add_f32_e32 v69, 1.0, v69
	v_rcp_f32_e32 v70, v69
	v_mul_f32_e32 v69, 0xbfb8aa3b, v77
	v_exp_f32_e32 v69, v69
	s_nop 0
	v_add_f32_e32 v69, 1.0, v69
	v_rcp_f32_e32 v71, v69
	s_nop 0
	v_pk_mul_f32 v[70:71], v[76:77], v[70:71]
	s_nop 0
	v_pk_mul_f32 v[70:71], v[84:85], v[70:71]
	s_nop 0
	v_cvt_pk_bf16_f32 v69, v70, v71
	global_store_dwordx4 v[82:83], v[66:69], off
	s_nop 1
	v_pk_mul_f32 v[68:69], v[52:53], v[182:183] op_sel_hi:[1,0]
	v_pk_mul_f32 v[52:53], v[50:51], v[182:183] op_sel_hi:[1,0]
	v_mul_f32_e32 v50, 0xbfb8aa3b, v62
	v_mul_f32_e32 v51, 0xbfb8aa3b, v63
	v_exp_f32_e32 v50, v50
	v_exp_f32_e32 v51, v51
	v_mad_i64_i32 v[66:67], s[4:5], v172, s6, v[132:133]
	v_add_f32_e32 v50, 1.0, v50
	v_add_f32_e32 v51, 1.0, v51
	v_rcp_f32_e32 v50, v50
	v_rcp_f32_e32 v51, v51
	s_nop 0
	v_pk_mul_f32 v[50:51], v[62:63], v[50:51]
	s_nop 0
	v_pk_mul_f32 v[50:51], v[54:55], v[50:51]
	s_nop 0
	v_cvt_pk_bf16_f32 v50, v50, v51
	v_mul_f32_e32 v51, 0xbfb8aa3b, v64
	v_exp_f32_e32 v51, v51
	s_nop 0
	v_add_f32_e32 v51, 1.0, v51
	v_rcp_f32_e32 v54, v51
	v_mul_f32_e32 v51, 0xbfb8aa3b, v65
	v_exp_f32_e32 v51, v51
	s_nop 0
	v_add_f32_e32 v51, 1.0, v51
	v_rcp_f32_e32 v55, v51
	s_nop 0
	v_pk_mul_f32 v[54:55], v[64:65], v[54:55]
	s_nop 0
	v_pk_mul_f32 v[54:55], v[56:57], v[54:55]
	s_nop 0
	v_cvt_pk_bf16_f32 v51, v54, v55
	v_mul_f32_e32 v54, 0xbfb8aa3b, v58
	v_mul_f32_e32 v55, 0xbfb8aa3b, v59
	v_exp_f32_e32 v54, v54
	v_exp_f32_e32 v55, v55
	v_add_f32_e32 v54, 1.0, v54
	v_add_f32_e32 v55, 1.0, v55
	v_rcp_f32_e32 v54, v54
	v_rcp_f32_e32 v55, v55
	s_nop 0
	v_pk_mul_f32 v[54:55], v[58:59], v[54:55]
	s_nop 0
	v_pk_mul_f32 v[52:53], v[52:53], v[54:55]
	s_nop 0
	v_cvt_pk_bf16_f32 v52, v52, v53
	v_mul_f32_e32 v53, 0xbfb8aa3b, v60
	v_exp_f32_e32 v53, v53
	s_nop 0
	v_add_f32_e32 v53, 1.0, v53
	v_rcp_f32_e32 v54, v53
	v_mul_f32_e32 v53, 0xbfb8aa3b, v61
	v_exp_f32_e32 v53, v53
	s_nop 0
	v_add_f32_e32 v53, 1.0, v53
	v_rcp_f32_e32 v55, v53
	s_nop 0
	v_pk_mul_f32 v[54:55], v[60:61], v[54:55]
	s_nop 0
	v_pk_mul_f32 v[54:55], v[68:69], v[54:55]
	s_nop 0
	v_cvt_pk_bf16_f32 v53, v54, v55
	global_store_dwordx4 v[66:67], v[50:53], off
	s_nop 1
	v_pk_mul_f32 v[52:53], v[36:37], v[186:187] op_sel_hi:[1,0]
	v_pk_mul_f32 v[36:37], v[34:35], v[186:187] op_sel_hi:[1,0]
	v_mul_f32_e32 v34, 0xbfb8aa3b, v46
	v_mul_f32_e32 v35, 0xbfb8aa3b, v47
	v_exp_f32_e32 v34, v34
	v_exp_f32_e32 v35, v35
	v_mad_i64_i32 v[50:51], s[4:5], v184, s6, v[132:133]
	v_add_f32_e32 v34, 1.0, v34
	v_add_f32_e32 v35, 1.0, v35
	v_rcp_f32_e32 v34, v34
	v_rcp_f32_e32 v35, v35
	s_nop 0
	v_pk_mul_f32 v[34:35], v[46:47], v[34:35]
	s_nop 0
	v_pk_mul_f32 v[34:35], v[38:39], v[34:35]
	s_nop 0
	v_cvt_pk_bf16_f32 v34, v34, v35
	v_mul_f32_e32 v35, 0xbfb8aa3b, v48
	v_exp_f32_e32 v35, v35
	s_nop 0
	v_add_f32_e32 v35, 1.0, v35
	v_rcp_f32_e32 v38, v35
	v_mul_f32_e32 v35, 0xbfb8aa3b, v49
	v_exp_f32_e32 v35, v35
	s_nop 0
	v_add_f32_e32 v35, 1.0, v35
	v_rcp_f32_e32 v39, v35
	s_nop 0
	v_pk_mul_f32 v[38:39], v[48:49], v[38:39]
	s_nop 0
	v_pk_mul_f32 v[38:39], v[40:41], v[38:39]
	s_nop 0
	v_cvt_pk_bf16_f32 v35, v38, v39
	v_mul_f32_e32 v38, 0xbfb8aa3b, v42
	v_mul_f32_e32 v39, 0xbfb8aa3b, v43
	v_exp_f32_e32 v38, v38
	v_exp_f32_e32 v39, v39
	v_add_f32_e32 v38, 1.0, v38
	v_add_f32_e32 v39, 1.0, v39
	v_rcp_f32_e32 v38, v38
	v_rcp_f32_e32 v39, v39
	s_nop 0
	v_pk_mul_f32 v[38:39], v[42:43], v[38:39]
	s_nop 0
	v_pk_mul_f32 v[36:37], v[36:37], v[38:39]
	s_nop 0
	v_cvt_pk_bf16_f32 v36, v36, v37
	v_mul_f32_e32 v37, 0xbfb8aa3b, v44
	v_exp_f32_e32 v37, v37
	s_nop 0
	v_add_f32_e32 v37, 1.0, v37
	v_rcp_f32_e32 v38, v37
	v_mul_f32_e32 v37, 0xbfb8aa3b, v45
	v_exp_f32_e32 v37, v37
	s_nop 0
	v_add_f32_e32 v37, 1.0, v37
	v_rcp_f32_e32 v39, v37
	s_nop 0
	v_pk_mul_f32 v[38:39], v[44:45], v[38:39]
	s_nop 0
	v_pk_mul_f32 v[38:39], v[52:53], v[38:39]
	s_nop 0
	v_cvt_pk_bf16_f32 v37, v38, v39
	global_store_dwordx4 v[50:51], v[34:37], off
	s_nop 1
	v_pk_mul_f32 v[36:37], v[20:21], v[190:191] op_sel_hi:[1,0]
	v_pk_mul_f32 v[20:21], v[18:19], v[190:191] op_sel_hi:[1,0]
	v_mul_f32_e32 v18, 0xbfb8aa3b, v30
	v_mul_f32_e32 v19, 0xbfb8aa3b, v31
	v_exp_f32_e32 v18, v18
	v_exp_f32_e32 v19, v19
	v_mad_i64_i32 v[34:35], s[4:5], v188, s6, v[132:133]
	v_add_f32_e32 v18, 1.0, v18
	v_add_f32_e32 v19, 1.0, v19
	v_rcp_f32_e32 v18, v18
	v_rcp_f32_e32 v19, v19
	s_nop 0
	v_pk_mul_f32 v[18:19], v[30:31], v[18:19]
	s_nop 0
	v_pk_mul_f32 v[18:19], v[22:23], v[18:19]
	s_nop 0
	v_cvt_pk_bf16_f32 v18, v18, v19
	v_mul_f32_e32 v19, 0xbfb8aa3b, v32
	v_exp_f32_e32 v19, v19
	s_nop 0
	v_add_f32_e32 v19, 1.0, v19
	v_rcp_f32_e32 v22, v19
	v_mul_f32_e32 v19, 0xbfb8aa3b, v33
	v_exp_f32_e32 v19, v19
	s_nop 0
	v_add_f32_e32 v19, 1.0, v19
	v_rcp_f32_e32 v23, v19
	s_nop 0
	v_pk_mul_f32 v[22:23], v[32:33], v[22:23]
	s_nop 0
	v_pk_mul_f32 v[22:23], v[24:25], v[22:23]
	s_nop 0
	v_cvt_pk_bf16_f32 v19, v22, v23
	v_mul_f32_e32 v22, 0xbfb8aa3b, v26
	v_mul_f32_e32 v23, 0xbfb8aa3b, v27
	v_exp_f32_e32 v22, v22
	v_exp_f32_e32 v23, v23
	v_add_f32_e32 v22, 1.0, v22
	v_add_f32_e32 v23, 1.0, v23
	v_rcp_f32_e32 v22, v22
	v_rcp_f32_e32 v23, v23
	s_nop 0
	v_pk_mul_f32 v[22:23], v[26:27], v[22:23]
	s_nop 0
	v_pk_mul_f32 v[20:21], v[20:21], v[22:23]
	s_nop 0
	v_cvt_pk_bf16_f32 v20, v20, v21
	v_mul_f32_e32 v21, 0xbfb8aa3b, v28
	v_exp_f32_e32 v21, v21
	s_nop 0
	v_add_f32_e32 v21, 1.0, v21
	v_rcp_f32_e32 v22, v21
	v_mul_f32_e32 v21, 0xbfb8aa3b, v29
	v_exp_f32_e32 v21, v21
	s_nop 0
	v_add_f32_e32 v21, 1.0, v21
	v_rcp_f32_e32 v23, v21
	s_nop 0
	v_pk_mul_f32 v[22:23], v[28:29], v[22:23]
	s_nop 0
	v_pk_mul_f32 v[22:23], v[36:37], v[22:23]
	s_nop 0
	v_cvt_pk_bf16_f32 v21, v22, v23
	global_store_dwordx4 v[34:35], v[18:21], off
	s_nop 1
	v_pk_mul_f32 v[20:21], v[4:5], v[130:131] op_sel_hi:[1,0]
	v_pk_mul_f32 v[4:5], v[2:3], v[130:131] op_sel_hi:[1,0]
	v_mul_f32_e32 v2, 0xbfb8aa3b, v14
	v_mul_f32_e32 v3, 0xbfb8aa3b, v15
	v_exp_f32_e32 v2, v2
	v_exp_f32_e32 v3, v3
	v_mad_i64_i32 v[18:19], s[4:5], v192, s6, v[132:133]
	v_add_f32_e32 v2, 1.0, v2
	v_add_f32_e32 v3, 1.0, v3
	v_rcp_f32_e32 v2, v2
	v_rcp_f32_e32 v3, v3
	s_mov_b64 s[6:7], -1
	v_pk_mul_f32 v[2:3], v[14:15], v[2:3]
	s_nop 0
	v_pk_mul_f32 v[2:3], v[6:7], v[2:3]
	s_nop 0
	v_cvt_pk_bf16_f32 v2, v2, v3
	v_mul_f32_e32 v3, 0xbfb8aa3b, v16
	v_exp_f32_e32 v3, v3
	s_nop 0
	v_add_f32_e32 v3, 1.0, v3
	v_rcp_f32_e32 v6, v3
	v_mul_f32_e32 v3, 0xbfb8aa3b, v17
	v_exp_f32_e32 v3, v3
	s_nop 0
	v_add_f32_e32 v3, 1.0, v3
	v_rcp_f32_e32 v7, v3
	s_nop 0
	v_pk_mul_f32 v[6:7], v[16:17], v[6:7]
	s_nop 0
	v_pk_mul_f32 v[6:7], v[8:9], v[6:7]
	s_nop 0
	v_cvt_pk_bf16_f32 v3, v6, v7
	v_mul_f32_e32 v6, 0xbfb8aa3b, v10
	v_mul_f32_e32 v7, 0xbfb8aa3b, v11
	v_exp_f32_e32 v6, v6
	v_exp_f32_e32 v7, v7
	v_add_f32_e32 v6, 1.0, v6
	v_add_f32_e32 v7, 1.0, v7
	v_rcp_f32_e32 v6, v6
	v_rcp_f32_e32 v7, v7
	s_nop 0
	v_pk_mul_f32 v[6:7], v[10:11], v[6:7]
	s_nop 0
	v_pk_mul_f32 v[4:5], v[4:5], v[6:7]
	s_nop 0
	v_cvt_pk_bf16_f32 v4, v4, v5
	v_mul_f32_e32 v5, 0xbfb8aa3b, v12
	v_exp_f32_e32 v5, v5
	s_nop 0
	v_add_f32_e32 v5, 1.0, v5
	v_rcp_f32_e32 v6, v5
	v_mul_f32_e32 v5, 0xbfb8aa3b, v13
	v_exp_f32_e32 v5, v5
	s_nop 0
	v_add_f32_e32 v5, 1.0, v5
	v_rcp_f32_e32 v7, v5
	s_nop 0
	v_pk_mul_f32 v[6:7], v[12:13], v[6:7]
	s_nop 0
	v_pk_mul_f32 v[6:7], v[20:21], v[6:7]
	s_nop 0
	v_cvt_pk_bf16_f32 v5, v6, v7
	global_store_dwordx4 v[18:19], v[2:5], off
	s_cbranch_vccnz .LBB0_600
	s_andn2_b64 vcc, exec, s[10:11]
	s_cbranch_vccnz .LBB0_599
	s_barrier
	s_branch .LBB0_599
